# PV pipelining plus: softmax row-sum adds moved into the last PV k-step's MFMA gaps, K-fragment LDS reads issued before the tile DMA block
# speedup vs baseline: 1.0101x; 1.0039x over previous
.LBB0_570:
	s_waitcnt lgkmcnt(0)
	v_lshl_add_u32 v157, s81, 13, v132
	ds_read_b128 v[192:195], v157
	ds_read_b128 v[200:203], v157 offset:2048
	ds_read_b128 v[208:211], v157 offset:4096
	ds_read_b128 v[220:223], v157 offset:6144
	ds_read_b128 v[196:199], v157 offset:512
	ds_read_b128 v[204:207], v157 offset:2560
	ds_read_b128 v[212:215], v157 offset:4608
	ds_read_b128 v[228:231], v157 offset:6656
	s_add_i32 s8, s84, s83
	s_add_i32 s9, s84, s87
	s_add_i32 s10, s83, 2
	s_cmp_ge_i32 s10, s89
	s_cbranch_scc1 .LBB0_572
	v_sub_co_u32_e64 v66, s[10:11], s81, 1
	s_nop 1
	v_cndmask_b32_e64 v68, v66, 2, s[10:11]
	s_add_i32 s10, s8, 2
	s_add_i32 s11, s9, 1
	s_cmp_lt_u32 s83, 2
	s_cselect_b32 s10, s10, s11
	s_ashr_i32 s11, s10, 31
	v_lshlrev_b32_e32 v69, 13, v68
	s_lshl_b64 s[12:13], s[10:11], 13
	v_add_u32_e32 v69, s77, v69
	v_lshlrev_b32_e32 v68, 14, v68
	v_lshl_add_u64 v[66:67], v[122:123], 0, s[12:13]
	v_readfirstlane_b32 s12, v69
	s_mov_b32 s13, m0
	s_mov_b32 m0, s12
	s_nop 0
	global_load_lds_dwordx4 v[66:67], off
	s_mov_b32 m0, s13
	s_lshl_b64 s[10:11], s[10:11], 14
	v_add_u32_e32 v69, s76, v68
	v_lshl_add_u64 v[66:67], v[118:119], 0, s[10:11]
	v_readfirstlane_b32 s12, v69
	s_mov_b32 s13, m0
	s_mov_b32 m0, s12
	s_nop 0
	global_load_lds_dwordx4 v[66:67], off
	s_mov_b32 m0, s13
	v_add_u32_e32 v68, s88, v68
	v_lshl_add_u64 v[66:67], v[120:121], 0, s[10:11]
	v_readfirstlane_b32 s10, v68
	s_mov_b32 s11, m0
	s_mov_b32 m0, s10
	s_nop 0
	global_load_lds_dwordx4 v[66:67], off
	s_mov_b32 m0, s11
.LBB0_572:
	s_add_i32 s9, s9, 3
	s_cmp_lt_u32 s83, 4
	s_cselect_b32 s8, s8, s9
	v_lshl_add_u32 v156, s8, 6, v151
	v_cvt_f32_i32_e32 v66, v156
	s_cmp_lt_i32 s8, s84
	v_fma_f32 v81, v117, v66, -v155
	v_add_f32_e32 v97, v149, v81
	v_pk_add_f32 v[66:67], v[190:191], v[80:81] op_sel:[0,1] op_sel_hi:[1,1]
	v_pk_add_f32 v[68:69], v[134:135], v[80:81] op_sel:[0,1] op_sel_hi:[1,1]
	v_pk_add_f32 v[70:71], v[136:137], v[80:81] op_sel:[0,1] op_sel_hi:[1,1]
	v_pk_add_f32 v[72:73], v[138:139], v[80:81] op_sel:[0,1] op_sel_hi:[1,1]
	v_pk_add_f32 v[74:75], v[140:141], v[80:81] op_sel:[0,1] op_sel_hi:[1,1]
	v_pk_add_f32 v[76:77], v[142:143], v[80:81] op_sel:[0,1] op_sel_hi:[1,1]
	v_pk_add_f32 v[78:79], v[144:145], v[80:81] op_sel:[0,1] op_sel_hi:[1,1]
	v_pk_add_f32 v[80:81], v[216:217], v[80:81] op_sel:[0,1] op_sel_hi:[1,1]
	v_pk_add_f32 v[82:83], v[190:191], v[96:97] op_sel:[0,1] op_sel_hi:[1,1]
	v_pk_add_f32 v[84:85], v[134:135], v[96:97] op_sel:[0,1] op_sel_hi:[1,1]
	v_pk_add_f32 v[86:87], v[136:137], v[96:97] op_sel:[0,1] op_sel_hi:[1,1]
	v_pk_add_f32 v[88:89], v[138:139], v[96:97] op_sel:[0,1] op_sel_hi:[1,1]
	v_pk_add_f32 v[90:91], v[140:141], v[96:97] op_sel:[0,1] op_sel_hi:[1,1]
	v_pk_add_f32 v[92:93], v[142:143], v[96:97] op_sel:[0,1] op_sel_hi:[1,1]
	v_pk_add_f32 v[94:95], v[144:145], v[96:97] op_sel:[0,1] op_sel_hi:[1,1]
	v_pk_add_f32 v[96:97], v[216:217], v[96:97] op_sel:[0,1] op_sel_hi:[1,1]
	s_waitcnt lgkmcnt(4)
	v_mfma_f32_32x32x16_bf16 v[66:81], v[192:195], v[98:101], v[66:81]
	v_mfma_f32_32x32x16_bf16 v[66:81], v[200:203], v[102:105], v[66:81]
	v_mfma_f32_32x32x16_bf16 v[66:81], v[208:211], v[106:109], v[66:81]
	v_mfma_f32_32x32x16_bf16 v[66:81], v[220:223], v[110:113], v[66:81]
	s_waitcnt lgkmcnt(0)
	s_nop 1
	v_mfma_f32_32x32x16_bf16 v[82:97], v[196:199], v[98:101], v[82:97]
	v_mfma_f32_32x32x16_bf16 v[82:97], v[204:207], v[102:105], v[82:97]
	v_mfma_f32_32x32x16_bf16 v[82:97], v[212:215], v[106:109], v[82:97]
	v_mfma_f32_32x32x16_bf16 v[82:97], v[228:231], v[110:113], v[82:97]
	s_cbranch_scc1 .LBB0_574
	s_movk_i32 s36, 0xffe6
	s_movk_i32 s64, 0xffe5
	s_movk_i32 s34, 0xffe7
	v_cmp_lt_i32_e64 s[62:63], s36, v156
	v_cmp_lt_i32_e64 s[64:65], s64, v156
	s_movk_i32 s30, 0xffe8
	v_cmp_lt_i32_e64 s[60:61], s34, v156
	s_and_b64 s[62:63], s[64:65], s[62:63]
	s_movk_i32 s28, 0xffed
	v_cmp_lt_i32_e64 s[58:59], s30, v156
	s_and_b64 s[60:61], s[62:63], s[60:61]
	s_movk_i32 s26, 0xffee
	v_cmp_lt_i32_e64 s[56:57], s28, v156
	s_and_b64 s[58:59], s[60:61], s[58:59]
	s_movk_i32 s24, 0xffef
	v_cmp_lt_i32_e64 s[54:55], s26, v156
	s_and_b64 s[56:57], s[58:59], s[56:57]
	v_cmp_lt_i32_e64 s[52:53], s24, v156
	s_and_b64 s[54:55], s[56:57], s[54:55]
	v_cmp_lt_i32_e64 s[50:51], -16, v156
	s_and_b64 s[52:53], s[54:55], s[52:53]
	v_cmp_lt_i32_e64 s[48:49], -11, v156
	s_and_b64 s[50:51], s[52:53], s[50:51]
	v_cmp_lt_i32_e64 s[46:47], -10, v156
	s_and_b64 s[48:49], s[50:51], s[48:49]
	v_cmp_lt_i32_e64 s[44:45], -9, v156
	s_and_b64 s[46:47], s[48:49], s[46:47]
	s_movk_i32 s10, 0xffe0
	v_cmp_lt_i32_e64 s[42:43], -8, v156
	s_and_b64 s[44:45], s[46:47], s[44:45]
	v_cmp_gt_i32_e64 s[8:9], 1, v156
	v_cmp_lt_i32_e32 vcc, s10, v156
	v_cmp_gt_i32_e64 s[10:11], 0, v156
	v_cmp_lt_i32_e64 s[40:41], -3, v156
	s_and_b64 s[42:43], s[44:45], s[42:43]
	s_or_b64 s[8:9], s[10:11], s[8:9]
	v_cmp_lt_i32_e64 s[38:39], -2, v156
	s_and_b64 s[40:41], s[42:43], s[40:41]
	v_cndmask_b32_e64 v157, v127, v67, s[10:11]
	v_cndmask_b32_e64 v158, v127, v66, s[8:9]
	s_and_b64 s[38:39], s[40:41], s[38:39]
	s_movk_i32 s36, 0xffc6
	v_cndmask_b32_e64 v66, v66, v158, s[38:39]
	v_cndmask_b32_e64 v68, v68, v127, s[38:39]
	v_cndmask_b32_e64 v67, v67, v157, s[38:39]
	s_movk_i32 s38, 0xffc5
	s_movk_i32 s34, 0xffc7
	v_cmp_lt_i32_e64 s[36:37], s36, v156
	v_cmp_lt_i32_e64 s[38:39], s38, v156
	s_movk_i32 s30, 0xffc8
	v_cmp_lt_i32_e64 s[34:35], s34, v156
	s_and_b64 s[36:37], s[38:39], s[36:37]
	s_movk_i32 s28, 0xffcd
	v_cmp_lt_i32_e64 s[30:31], s30, v156
	s_and_b64 s[34:35], s[36:37], s[34:35]
	s_movk_i32 s26, 0xffce
	v_cmp_lt_i32_e64 s[28:29], s28, v156
	s_and_b64 s[30:31], s[34:35], s[30:31]
	s_movk_i32 s24, 0xffcf
	v_cmp_lt_i32_e64 s[26:27], s26, v156
	s_and_b64 s[28:29], s[30:31], s[28:29]
	s_movk_i32 s22, 0xffd0
	v_cmp_lt_i32_e64 s[24:25], s24, v156
	s_and_b64 s[26:27], s[28:29], s[26:27]
	s_movk_i32 s20, 0xffd5
	v_cmp_lt_i32_e64 s[22:23], s22, v156
	s_and_b64 s[24:25], s[26:27], s[24:25]
	s_movk_i32 s18, 0xffd6
	v_cmp_lt_i32_e64 s[20:21], s20, v156
	s_and_b64 s[22:23], s[24:25], s[22:23]
	s_movk_i32 s16, 0xffd7
	v_cmp_lt_i32_e64 s[18:19], s18, v156
	s_and_b64 s[20:21], s[22:23], s[20:21]
	s_movk_i32 s14, 0xffd8
	v_cmp_lt_i32_e64 s[16:17], s16, v156
	s_and_b64 s[18:19], s[20:21], s[18:19]
	s_movk_i32 s12, 0xffdd
	v_cmp_lt_i32_e64 s[14:15], s14, v156
	s_and_b64 s[16:17], s[18:19], s[16:17]
	s_movk_i32 s10, 0xffde
	v_cmp_lt_i32_e64 s[12:13], s12, v156
	s_and_b64 s[14:15], s[16:17], s[14:15]
	s_movk_i32 s8, 0xffdf
	v_cmp_lt_i32_e64 s[10:11], s10, v156
	s_and_b64 s[12:13], s[14:15], s[12:13]
	v_cmp_lt_i32_e64 s[8:9], s8, v156
	s_and_b64 s[10:11], s[12:13], s[10:11]
	s_and_b64 s[8:9], s[10:11], s[8:9]
	s_and_b64 vcc, s[8:9], vcc
	v_cndmask_b32_e64 v81, v81, v127, s[64:65]
	v_cndmask_b32_e64 v80, v80, v127, s[62:63]
	v_cndmask_b32_e64 v79, v79, v127, s[60:61]
	v_cndmask_b32_e64 v78, v78, v127, s[58:59]
	v_cndmask_b32_e64 v77, v77, v127, s[56:57]
	v_cndmask_b32_e64 v76, v76, v127, s[54:55]
	v_cndmask_b32_e64 v75, v75, v127, s[52:53]
	v_cndmask_b32_e64 v74, v74, v127, s[50:51]
	v_cndmask_b32_e64 v73, v73, v127, s[48:49]
	v_cndmask_b32_e64 v72, v72, v127, s[46:47]
	v_cndmask_b32_e64 v71, v71, v127, s[44:45]
	v_cndmask_b32_e64 v70, v70, v127, s[42:43]
	v_cndmask_b32_e64 v69, v69, v127, s[40:41]
	v_cndmask_b32_e64 v97, v97, v127, s[38:39]
	v_cndmask_b32_e64 v96, v96, v127, s[36:37]
	v_cndmask_b32_e64 v95, v95, v127, s[34:35]
	v_cndmask_b32_e64 v94, v94, v127, s[30:31]
	v_cndmask_b32_e64 v93, v93, v127, s[28:29]
	v_cndmask_b32_e64 v92, v92, v127, s[26:27]
	v_cndmask_b32_e64 v91, v91, v127, s[24:25]
	v_cndmask_b32_e64 v90, v90, v127, s[22:23]
	v_cndmask_b32_e64 v89, v89, v127, s[20:21]
	v_cndmask_b32_e64 v88, v88, v127, s[18:19]
	v_cndmask_b32_e64 v87, v87, v127, s[16:17]
	v_cndmask_b32_e64 v86, v86, v127, s[14:15]
	v_cndmask_b32_e64 v85, v85, v127, s[12:13]
	v_cndmask_b32_e64 v84, v84, v127, s[10:11]
	v_cndmask_b32_e64 v83, v83, v127, s[8:9]
	v_cndmask_b32_e32 v82, v82, v127, vcc

.LBB0_582:
	v_lshl_add_u32 v188, s81, 14, v152
	ds_read_b64_tr_b16 v[172:173], v188 offset:0
	ds_read_b64_tr_b16 v[174:175], v188 offset:512
	ds_read_b64_tr_b16 v[176:177], v188 offset:4096
	ds_read_b64_tr_b16 v[178:179], v188 offset:4608
	ds_read_b64_tr_b16 v[180:181], v188 offset:8192
	ds_read_b64_tr_b16 v[182:183], v188 offset:8704
	ds_read_b64_tr_b16 v[184:185], v188 offset:12288
	ds_read_b64_tr_b16 v[186:187], v188 offset:12800
	ds_read_b64_tr_b16 v[192:193], v188 offset:1024
	ds_read_b64_tr_b16 v[194:195], v188 offset:1536
	ds_read_b64_tr_b16 v[196:197], v188 offset:5120
	ds_read_b64_tr_b16 v[198:199], v188 offset:5632
	ds_read_b64_tr_b16 v[200:201], v188 offset:9216
	ds_read_b64_tr_b16 v[202:203], v188 offset:9728
	ds_read_b64_tr_b16 v[204:205], v188 offset:13312
	ds_read_b64_tr_b16 v[206:207], v188 offset:13824
	v_exp_f32_e32 v66, v66
	v_exp_f32_e32 v67, v67
	v_exp_f32_e32 v68, v68
	v_exp_f32_e32 v69, v69
	v_exp_f32_e32 v70, v70
	v_exp_f32_e32 v71, v71
	v_exp_f32_e32 v72, v72
	v_exp_f32_e32 v73, v73
	v_cvt_pk_bf16_f32 v156, v66, v67
	v_cvt_pk_bf16_f32 v157, v68, v69
	v_cvt_pk_bf16_f32 v158, v70, v71
	v_cvt_pk_bf16_f32 v159, v72, v73
	s_waitcnt lgkmcnt(8)
	s_nop 1
	v_mfma_f32_32x32x16_bf16 v[2:17], v[156:159], v[172:175], v[2:17]
	v_exp_f32_e32 v74, v74
	v_exp_f32_e32 v75, v75
	v_mfma_f32_32x32x16_bf16 v[50:65], v[156:159], v[176:179], v[50:65]
	v_exp_f32_e32 v76, v76
	v_exp_f32_e32 v77, v77
	v_mfma_f32_32x32x16_bf16 v[34:49], v[156:159], v[180:183], v[34:49]
	v_exp_f32_e32 v78, v78
	v_exp_f32_e32 v79, v79
	v_mfma_f32_32x32x16_bf16 v[18:33], v[156:159], v[184:187], v[18:33]
	v_exp_f32_e32 v80, v80
	v_exp_f32_e32 v81, v81
	v_cvt_pk_bf16_f32 v160, v74, v75
	v_cvt_pk_bf16_f32 v161, v76, v77
	v_cvt_pk_bf16_f32 v162, v78, v79
	v_cvt_pk_bf16_f32 v163, v80, v81
	ds_read_b64_tr_b16 v[172:173], v188 offset:2048
	ds_read_b64_tr_b16 v[174:175], v188 offset:2560
	ds_read_b64_tr_b16 v[176:177], v188 offset:6144
	ds_read_b64_tr_b16 v[178:179], v188 offset:6656
	ds_read_b64_tr_b16 v[180:181], v188 offset:10240
	ds_read_b64_tr_b16 v[182:183], v188 offset:10752
	ds_read_b64_tr_b16 v[184:185], v188 offset:14336
	ds_read_b64_tr_b16 v[186:187], v188 offset:14848
	s_waitcnt lgkmcnt(8)
	s_nop 1
	v_mfma_f32_32x32x16_bf16 v[2:17], v[160:163], v[192:195], v[2:17]
	v_exp_f32_e32 v82, v82
	v_exp_f32_e32 v83, v83
	v_mfma_f32_32x32x16_bf16 v[50:65], v[160:163], v[196:199], v[50:65]
	v_exp_f32_e32 v84, v84
	v_exp_f32_e32 v85, v85
	v_mfma_f32_32x32x16_bf16 v[34:49], v[160:163], v[200:203], v[34:49]
	v_exp_f32_e32 v86, v86
	v_exp_f32_e32 v87, v87
	v_mfma_f32_32x32x16_bf16 v[18:33], v[160:163], v[204:207], v[18:33]
	v_exp_f32_e32 v88, v88
	v_exp_f32_e32 v89, v89
	v_cvt_pk_bf16_f32 v164, v82, v83
	v_cvt_pk_bf16_f32 v165, v84, v85
	v_cvt_pk_bf16_f32 v166, v86, v87
	v_cvt_pk_bf16_f32 v167, v88, v89
	ds_read_b64_tr_b16 v[192:193], v188 offset:3072
	ds_read_b64_tr_b16 v[194:195], v188 offset:3584
	ds_read_b64_tr_b16 v[196:197], v188 offset:7168
	ds_read_b64_tr_b16 v[198:199], v188 offset:7680
	ds_read_b64_tr_b16 v[200:201], v188 offset:11264
	ds_read_b64_tr_b16 v[202:203], v188 offset:11776
	ds_read_b64_tr_b16 v[204:205], v188 offset:15360
	ds_read_b64_tr_b16 v[206:207], v188 offset:15872
	s_waitcnt lgkmcnt(8)
	s_nop 1
	v_mfma_f32_32x32x16_bf16 v[2:17], v[164:167], v[172:175], v[2:17]
	v_exp_f32_e32 v90, v90
	v_exp_f32_e32 v91, v91
	v_mfma_f32_32x32x16_bf16 v[50:65], v[164:167], v[176:179], v[50:65]
	v_exp_f32_e32 v92, v92
	v_exp_f32_e32 v93, v93
	v_mfma_f32_32x32x16_bf16 v[34:49], v[164:167], v[180:183], v[34:49]
	v_exp_f32_e32 v94, v94
	v_exp_f32_e32 v95, v95
	v_mfma_f32_32x32x16_bf16 v[18:33], v[164:167], v[184:187], v[18:33]
	v_exp_f32_e32 v96, v96
	v_exp_f32_e32 v97, v97
	v_cvt_pk_bf16_f32 v168, v90, v91
	v_cvt_pk_bf16_f32 v169, v92, v93
	v_cvt_pk_bf16_f32 v170, v94, v95
	v_cvt_pk_bf16_f32 v171, v96, v97
	s_waitcnt lgkmcnt(0)
	s_nop 1
	v_mfma_f32_32x32x16_bf16 v[2:17], v[168:171], v[192:195], v[2:17]
	s_cmp_lt_u32 s83, 3
	v_add_f32_e32 v66, v82, v66
	v_add_f32_e32 v67, v83, v67
	v_add_f32_e32 v66, 0, v66
	v_add_f32_e32 v68, v84, v68
	v_add_f32_e32 v66, v67, v66
	v_add_f32_e32 v69, v85, v69
	v_add_f32_e32 v66, v68, v66
	v_add_f32_e32 v70, v86, v70
	v_mfma_f32_32x32x16_bf16 v[50:65], v[168:171], v[196:199], v[50:65]
	s_cselect_b64 s[8:9], -1, 0
	v_add_f32_e32 v66, v69, v66
	v_add_f32_e32 v71, v87, v71
	v_add_f32_e32 v66, v70, v66
	v_add_f32_e32 v72, v88, v72
	v_add_f32_e32 v66, v71, v66
	v_add_f32_e32 v73, v89, v73
	v_add_f32_e32 v66, v72, v66
	v_add_f32_e32 v74, v90, v74
	v_mfma_f32_32x32x16_bf16 v[34:49], v[168:171], v[200:203], v[34:49]
	s_or_b64 s[0:1], s[8:9], s[0:1]
	v_add_f32_e32 v66, v73, v66
	v_add_f32_e32 v75, v91, v75
	v_add_f32_e32 v66, v74, v66
	v_add_f32_e32 v76, v92, v76
	v_add_f32_e32 v66, v75, v66
	v_add_f32_e32 v77, v93, v77
	v_add_f32_e32 v66, v76, v66
	v_add_f32_e32 v78, v94, v78
	v_mfma_f32_32x32x16_bf16 v[18:33], v[168:171], v[204:207], v[18:33]
	s_and_b64 vcc, exec, s[0:1]
	v_add_f32_e32 v66, v77, v66
	v_add_f32_e32 v79, v95, v79
	v_add_f32_e32 v66, v78, v66
	v_add_f32_e32 v80, v96, v80
	v_add_f32_e32 v66, v79, v66
	v_add_f32_e32 v81, v97, v81
	v_add_f32_e32 v66, v80, v66
	v_add_f32_e32 v66, v81, v66
	v_add_f32_e32 v154, v154, v66
	s_cbranch_vccnz .LBB0_586
	v_cvt_f32_i32_e32 v156, v153
	v_fma_f32 v156, v117, v156, v150
	v_sub_f32_e32 v156, v156, v155
	s_nop 1
	v_max_f32_dpp v156, v156, v156 row_ror:1 row_mask:0xf bank_mask:0xf
	s_nop 1
	v_max_f32_dpp v156, v156, v156 row_ror:2 row_mask:0xf bank_mask:0xf
	s_nop 1
	v_max_f32_dpp v156, v156, v156 row_ror:4 row_mask:0xf bank_mask:0xf
	s_nop 1
	v_max_f32_dpp v156, v156, v156 row_ror:8 row_mask:0xf bank_mask:0xf
	s_nop 1
	v_readlane_b32 s9, v156, 16
	s_and_saveexec_b64 s[0:1], s[6:7]
	s_cbranch_execz .LBB0_585
	s_and_b32 s8, s80, 8
	s_lshl_b32 s8, s8, 2
	s_add_i32 s8, s68, s8
	v_max_f32_e32 v156, s9, v156
	v_mov_b32_e32 v157, s8
	ds_write_b32 v157, v156

.LBB0_586:
	s_add_i32 s0, s81, 1
	s_cmp_lg_u32 s81, 2
	s_cselect_b32 s81, s0, 0
	s_mov_b64 s[8:9], -1
